# nt hint removed from the FFN hidden-activation (ACT) stores of P1/P9 so P2/P10 read them from the memory-side cache
# speedup vs baseline: 1.0023x; 1.0023x over previous
; __device__ __forceinline__ unsigned pk2(float lo, float hi) { bf16x2_t r = __builtin_convertvector((f32x2_t){lo, hi}, bf16x2_t); return __builtin_bit_cast(unsigned, r); }
; __device__ __forceinline__ float sigmoid_fast(float x) { return __builtin_amdgcn_rcpf(1.0f + __builtin_amdgcn_exp2f(-1.44269504089f * x)); }
;     __device__ __forceinline__ void operator()(const pg8::f32x4 (&acc)[2][2][4][2], const pg8::Unit& u, int wr, int wc, int fr, int fq) const {
;         const int row0 = u.pm * 256 + wr * 64 + fr, col0 = u.pn * 128 + wc * 32 + 8 * fq;
;         float rvs[2][4]; rs_rows(lds, rs, u.pm, wr, fr, rvs);
; #pragma unroll
;         for (int ai = 0; ai < 2; ++ai)
; #pragma unroll
;             for (int m = 0; m < 4; ++m) {
;                 const float rv = rvs[ai][m];
;                 bf16* p = O + (size_t)(row0 + ai * 128 + m * 16) * FF + col0;
;                 const pg8::f32x4 g0 = acc[ai][0][m][0] * rv, g1 = acc[ai][0][m][1] * rv, u0 = acc[ai][1][m][0] * rv, u1 = acc[ai][1][m][1] * rv;
;                 float r[8];
; #pragma unroll
;                 for (int j = 0; j < 4; ++j) { r[j] = g0[j] * sigmoid_fast(g0[j]) * u0[j]; r[4 + j] = g1[j] * sigmoid_fast(g1[j]) * u1[j]; }
;                 v4u w; w.x = pk2(r[0], r[1]); w.y = pk2(r[2], r[3]); w.z = pk2(r[4], r[5]); w.w = pk2(r[6], r[7]);
;                 __builtin_nontemporal_store(w, (v4u*)p);
;             }
.LBB0_253:
	s_waitcnt vmcnt(0)
	v_pk_mul_f32 v[124:125], v[124:125], v[162:163] op_sel_hi:[1,0]
	v_mov_b64_e32 v[150:151], s[16:17]
	v_mul_f32_e32 v147, 0xbfb8aa3b, v124
	v_exp_f32_e32 v147, v147
	v_mul_f32_e32 v149, 0xbfb8aa3b, v125
	v_exp_f32_e32 v149, v149
	v_mad_u64_u32 v[172:173], s[36:37], v164, s63, v[150:151]
	v_mov_b32_e32 v164, v173
	v_mad_u64_u32 v[164:165], s[36:37], v165, s63, v[164:165]
	v_add_f32_e32 v147, 1.0, v147
	v_pk_mul_f32 v[120:121], v[120:121], v[162:163] op_sel_hi:[1,0]
	v_mov_b32_e32 v173, v164
	v_rcp_f32_e32 v164, v147
	v_add_f32_e32 v147, 1.0, v149
	v_mul_f32_e32 v149, 0xbfb8aa3b, v120
	v_exp_f32_e32 v149, v149
	v_mul_f32_e32 v155, 0xbfb8aa3b, v121
	v_rcp_f32_e32 v165, v147
	v_exp_f32_e32 v155, v155
	v_add_f32_e32 v147, 1.0, v149
	v_pk_mul_f32 v[116:117], v[116:117], v[162:163] op_sel_hi:[1,0]
	v_pk_mul_f32 v[124:125], v[124:125], v[164:165]
	v_rcp_f32_e32 v174, v147
	v_add_f32_e32 v147, 1.0, v155
	v_pk_mul_f32 v[116:117], v[116:117], v[124:125]
	v_pk_mul_f32 v[124:125], v[126:127], v[162:163] op_sel_hi:[1,0]
	v_rcp_f32_e32 v175, v147
	v_mul_f32_e32 v126, 0xbfb8aa3b, v124
	v_mul_f32_e32 v127, 0xbfb8aa3b, v125
	v_exp_f32_e32 v126, v126
	v_exp_f32_e32 v127, v127
	v_pk_mul_f32 v[120:121], v[120:121], v[174:175]
	v_pk_mul_f32 v[112:113], v[112:113], v[162:163] op_sel_hi:[1,0]
	v_pk_mul_f32 v[122:123], v[122:123], v[162:163] op_sel_hi:[1,0]
	v_pk_mul_f32 v[120:121], v[112:113], v[120:121]
	v_add_f32_e32 v112, 1.0, v126
	v_add_f32_e32 v113, 1.0, v127
	v_mul_f32_e32 v126, 0xbfb8aa3b, v122
	v_mul_f32_e32 v127, 0xbfb8aa3b, v123
	v_exp_f32_e32 v126, v126
	v_exp_f32_e32 v127, v127
	v_rcp_f32_e32 v112, v112
	v_rcp_f32_e32 v113, v113
	v_add_f32_e32 v126, 1.0, v126
	v_add_f32_e32 v127, 1.0, v127
	v_rcp_f32_e32 v126, v126
	v_rcp_f32_e32 v127, v127
	v_lshl_or_b32 v170, s66, 7, v161
	v_pk_mul_f32 v[112:113], v[124:125], v[112:113]
	v_pk_mul_f32 v[118:119], v[118:119], v[162:163] op_sel_hi:[1,0]
	v_ashrrev_i32_e32 v171, 31, v170
	v_pk_mul_f32 v[118:119], v[118:119], v[112:113]
	v_pk_mul_f32 v[112:113], v[122:123], v[126:127]
	v_pk_mul_f32 v[114:115], v[114:115], v[162:163] op_sel_hi:[1,0]
	v_pk_mul_f32 v[108:109], v[108:109], v[160:161] op_sel_hi:[1,0]
	v_pk_mul_f32 v[122:123], v[114:115], v[112:113]
	v_lshlrev_b64 v[112:113], 1, v[170:171]
	v_lshl_add_u64 v[124:125], v[172:173], 0, v[112:113]
	v_cvt_pk_bf16_f32 v114, v116, v117
	v_cvt_pk_bf16_f32 v115, v118, v119
	v_cvt_pk_bf16_f32 v116, v120, v121
	v_cvt_pk_bf16_f32 v117, v122, v123
	global_store_dwordx4 v[124:125], v[114:117], off
	v_pk_mul_f32 v[104:105], v[104:105], v[160:161] op_sel_hi:[1,0]
	v_pk_mul_f32 v[100:101], v[100:101], v[160:161] op_sel_hi:[1,0]
	v_mul_f32_e32 v115, 0xbfb8aa3b, v108
	v_exp_f32_e32 v116, v115
	v_mul_f32_e32 v115, 0xbfb8aa3b, v109
	v_exp_f32_e32 v117, v115
	v_mul_f32_e32 v118, 0xbfb8aa3b, v104
	v_add_f32_e32 v116, 1.0, v116
	v_rcp_f32_e32 v116, v116
	v_add_f32_e32 v117, 1.0, v117
	v_mul_f32_e32 v119, 0xbfb8aa3b, v105
	v_rcp_f32_e32 v117, v117
	v_exp_f32_e32 v118, v118
	v_exp_f32_e32 v119, v119
	v_pk_mul_f32 v[96:97], v[96:97], v[160:161] op_sel_hi:[1,0]
	v_pk_mul_f32 v[108:109], v[108:109], v[116:117]
	v_add_f32_e32 v118, 1.0, v118
	v_add_f32_e32 v119, 1.0, v119
	v_pk_mul_f32 v[100:101], v[100:101], v[108:109]
	v_pk_mul_f32 v[108:109], v[110:111], v[160:161] op_sel_hi:[1,0]
	v_rcp_f32_e32 v118, v118
	v_rcp_f32_e32 v119, v119
	v_mul_f32_e32 v110, 0xbfb8aa3b, v108
	v_mul_f32_e32 v111, 0xbfb8aa3b, v109
	v_exp_f32_e32 v110, v110
	v_exp_f32_e32 v111, v111
	v_pk_mul_f32 v[104:105], v[104:105], v[118:119]
	v_pk_mul_f32 v[106:107], v[106:107], v[160:161] op_sel_hi:[1,0]
	v_pk_mul_f32 v[104:105], v[96:97], v[104:105]
	v_add_f32_e32 v96, 1.0, v110
	v_add_f32_e32 v97, 1.0, v111
	v_mul_f32_e32 v110, 0xbfb8aa3b, v106
	v_mul_f32_e32 v111, 0xbfb8aa3b, v107
	v_exp_f32_e32 v110, v110
	v_exp_f32_e32 v111, v111
	v_rcp_f32_e32 v96, v96
	v_rcp_f32_e32 v97, v97
	v_add_f32_e32 v110, 1.0, v110
	v_add_f32_e32 v111, 1.0, v111
	v_rcp_f32_e32 v110, v110
	v_rcp_f32_e32 v111, v111
	v_pk_mul_f32 v[96:97], v[108:109], v[96:97]
	v_pk_mul_f32 v[102:103], v[102:103], v[160:161] op_sel_hi:[1,0]
	v_or_b32_e32 v114, 16, v146
	v_pk_mul_f32 v[102:103], v[102:103], v[96:97]
	v_pk_mul_f32 v[96:97], v[106:107], v[110:111]
	v_pk_mul_f32 v[98:99], v[98:99], v[160:161] op_sel_hi:[1,0]
	v_mad_i64_i32 v[114:115], s[36:37], v114, s63, v[150:151]
	v_pk_mul_f32 v[106:107], v[98:99], v[96:97]
	v_lshl_add_u64 v[108:109], v[114:115], 0, v[112:113]
	v_cvt_pk_bf16_f32 v96, v100, v101
	v_cvt_pk_bf16_f32 v97, v102, v103
	v_cvt_pk_bf16_f32 v98, v104, v105
	v_cvt_pk_bf16_f32 v99, v106, v107
	v_pk_mul_f32 v[92:93], v[92:93], v[158:159] op_sel_hi:[1,0]
	global_store_dwordx4 v[108:109], v[96:99], off
	v_pk_mul_f32 v[88:89], v[88:89], v[158:159] op_sel_hi:[1,0]
	v_pk_mul_f32 v[84:85], v[84:85], v[158:159] op_sel_hi:[1,0]
	v_mul_f32_e32 v97, 0xbfb8aa3b, v92
	v_exp_f32_e32 v98, v97
	v_mul_f32_e32 v97, 0xbfb8aa3b, v93
	v_exp_f32_e32 v99, v97
	v_mul_f32_e32 v100, 0xbfb8aa3b, v88
	v_add_f32_e32 v98, 1.0, v98
	v_rcp_f32_e32 v98, v98
	v_add_f32_e32 v99, 1.0, v99
	v_mul_f32_e32 v101, 0xbfb8aa3b, v89
	v_rcp_f32_e32 v99, v99
	v_exp_f32_e32 v100, v100
	v_exp_f32_e32 v101, v101
	v_pk_mul_f32 v[80:81], v[80:81], v[158:159] op_sel_hi:[1,0]
	v_pk_mul_f32 v[92:93], v[92:93], v[98:99]
	v_add_f32_e32 v100, 1.0, v100
	v_add_f32_e32 v101, 1.0, v101
	v_pk_mul_f32 v[84:85], v[84:85], v[92:93]
	v_pk_mul_f32 v[92:93], v[94:95], v[158:159] op_sel_hi:[1,0]
	v_rcp_f32_e32 v100, v100
	v_rcp_f32_e32 v101, v101
	v_mul_f32_e32 v94, 0xbfb8aa3b, v92
	v_mul_f32_e32 v95, 0xbfb8aa3b, v93
	v_exp_f32_e32 v94, v94
	v_exp_f32_e32 v95, v95
; __device__ __forceinline__ unsigned pk2(float lo, float hi) { bf16x2_t r = __builtin_convertvector((f32x2_t){lo, hi}, bf16x2_t); return __builtin_bit_cast(unsigned, r); }
; __device__ __forceinline__ float sigmoid_fast(float x) { return __builtin_amdgcn_rcpf(1.0f + __builtin_amdgcn_exp2f(-1.44269504089f * x)); }
;     __device__ __forceinline__ void operator()(const pg8::f32x4 (&acc)[2][2][4][2], const pg8::Unit& u, int wr, int wc, int fr, int fq) const {
;     ...
;                 const float rv = rvs[ai][m];
;                 bf16* p = O + (size_t)(row0 + ai * 128 + m * 16) * FF + col0;
;                 const pg8::f32x4 g0 = acc[ai][0][m][0] * rv, g1 = acc[ai][0][m][1] * rv, u0 = acc[ai][1][m][0] * rv, u1 = acc[ai][1][m][1] * rv;
;                 float r[8];
; #pragma unroll
;                 for (int j = 0; j < 4; ++j) { r[j] = g0[j] * sigmoid_fast(g0[j]) * u0[j]; r[4 + j] = g1[j] * sigmoid_fast(g1[j]) * u1[j]; }
;                 v4u w; w.x = pk2(r[0], r[1]); w.y = pk2(r[2], r[3]); w.z = pk2(r[4], r[5]); w.w = pk2(r[6], r[7]);
;                 __builtin_nontemporal_store(w, (v4u*)p);
	v_pk_mul_f32 v[88:89], v[88:89], v[100:101]
	v_pk_mul_f32 v[90:91], v[90:91], v[158:159] op_sel_hi:[1,0]
	v_pk_mul_f32 v[88:89], v[80:81], v[88:89]
	v_add_f32_e32 v80, 1.0, v94
	v_add_f32_e32 v81, 1.0, v95
	v_mul_f32_e32 v94, 0xbfb8aa3b, v90
	v_mul_f32_e32 v95, 0xbfb8aa3b, v91
	v_exp_f32_e32 v94, v94
	v_exp_f32_e32 v95, v95
	v_rcp_f32_e32 v80, v80
	v_rcp_f32_e32 v81, v81
	v_add_f32_e32 v94, 1.0, v94
	v_add_f32_e32 v95, 1.0, v95
	v_rcp_f32_e32 v94, v94
	v_rcp_f32_e32 v95, v95
	v_pk_mul_f32 v[80:81], v[92:93], v[80:81]
	v_pk_mul_f32 v[86:87], v[86:87], v[158:159] op_sel_hi:[1,0]
	v_or_b32_e32 v96, 32, v146
	v_pk_mul_f32 v[86:87], v[86:87], v[80:81]
	v_pk_mul_f32 v[80:81], v[90:91], v[94:95]
	v_pk_mul_f32 v[82:83], v[82:83], v[158:159] op_sel_hi:[1,0]
	v_mad_i64_i32 v[96:97], s[36:37], v96, s63, v[150:151]
	v_pk_mul_f32 v[90:91], v[82:83], v[80:81]
	v_lshl_add_u64 v[92:93], v[96:97], 0, v[112:113]
	v_cvt_pk_bf16_f32 v80, v84, v85
	v_cvt_pk_bf16_f32 v81, v86, v87
	v_cvt_pk_bf16_f32 v82, v88, v89
	v_cvt_pk_bf16_f32 v83, v90, v91
	v_pk_mul_f32 v[76:77], v[76:77], v[156:157] op_sel_hi:[1,0]
	global_store_dwordx4 v[92:93], v[80:83], off
	v_pk_mul_f32 v[72:73], v[72:73], v[156:157] op_sel_hi:[1,0]
	v_pk_mul_f32 v[68:69], v[68:69], v[156:157] op_sel_hi:[1,0]
	v_mul_f32_e32 v81, 0xbfb8aa3b, v76
	v_exp_f32_e32 v82, v81
	v_mul_f32_e32 v81, 0xbfb8aa3b, v77
	v_exp_f32_e32 v83, v81
	v_mul_f32_e32 v84, 0xbfb8aa3b, v72
	v_add_f32_e32 v82, 1.0, v82
	v_rcp_f32_e32 v82, v82
	v_add_f32_e32 v83, 1.0, v83
	v_mul_f32_e32 v85, 0xbfb8aa3b, v73
	v_rcp_f32_e32 v83, v83
	v_exp_f32_e32 v84, v84
	v_exp_f32_e32 v85, v85
	v_pk_mul_f32 v[64:65], v[64:65], v[156:157] op_sel_hi:[1,0]
	v_pk_mul_f32 v[76:77], v[76:77], v[82:83]
	v_add_f32_e32 v84, 1.0, v84
	v_add_f32_e32 v85, 1.0, v85
	v_pk_mul_f32 v[68:69], v[68:69], v[76:77]
	v_pk_mul_f32 v[76:77], v[78:79], v[156:157] op_sel_hi:[1,0]
	v_rcp_f32_e32 v84, v84
	v_rcp_f32_e32 v85, v85
	v_mul_f32_e32 v78, 0xbfb8aa3b, v76
	v_mul_f32_e32 v79, 0xbfb8aa3b, v77
	v_exp_f32_e32 v78, v78
	v_exp_f32_e32 v79, v79
	v_pk_mul_f32 v[72:73], v[72:73], v[84:85]
	v_pk_mul_f32 v[74:75], v[74:75], v[156:157] op_sel_hi:[1,0]
	v_pk_mul_f32 v[72:73], v[64:65], v[72:73]
	v_add_f32_e32 v64, 1.0, v78
	v_add_f32_e32 v65, 1.0, v79
	v_mul_f32_e32 v78, 0xbfb8aa3b, v74
	v_mul_f32_e32 v79, 0xbfb8aa3b, v75
	v_exp_f32_e32 v78, v78
	v_exp_f32_e32 v79, v79
	v_rcp_f32_e32 v64, v64
	v_rcp_f32_e32 v65, v65
	v_add_f32_e32 v78, 1.0, v78
	v_add_f32_e32 v79, 1.0, v79
	v_rcp_f32_e32 v78, v78
	v_rcp_f32_e32 v79, v79
	v_pk_mul_f32 v[64:65], v[76:77], v[64:65]
	v_pk_mul_f32 v[70:71], v[70:71], v[156:157] op_sel_hi:[1,0]
	v_or_b32_e32 v80, 48, v146
	v_pk_mul_f32 v[70:71], v[70:71], v[64:65]
	v_pk_mul_f32 v[64:65], v[74:75], v[78:79]
	v_pk_mul_f32 v[66:67], v[66:67], v[156:157] op_sel_hi:[1,0]
	v_mad_i64_i32 v[80:81], s[36:37], v80, s63, v[150:151]
	v_pk_mul_f32 v[74:75], v[66:67], v[64:65]
	v_lshl_add_u64 v[76:77], v[80:81], 0, v[112:113]
	v_cvt_pk_bf16_f32 v64, v68, v69
	v_cvt_pk_bf16_f32 v65, v70, v71
	v_cvt_pk_bf16_f32 v66, v72, v73
	v_cvt_pk_bf16_f32 v67, v74, v75
	v_pk_mul_f32 v[60:61], v[60:61], v[154:155] op_sel_hi:[1,0]
	global_store_dwordx4 v[76:77], v[64:67], off
	v_pk_mul_f32 v[56:57], v[56:57], v[154:155] op_sel_hi:[1,0]
	v_pk_mul_f32 v[52:53], v[52:53], v[154:155] op_sel_hi:[1,0]
	v_mul_f32_e32 v65, 0xbfb8aa3b, v60
	v_exp_f32_e32 v66, v65
	v_mul_f32_e32 v65, 0xbfb8aa3b, v61
	v_exp_f32_e32 v67, v65
	v_mul_f32_e32 v68, 0xbfb8aa3b, v56
	v_add_f32_e32 v66, 1.0, v66
	v_rcp_f32_e32 v66, v66
	v_add_f32_e32 v67, 1.0, v67
	v_mul_f32_e32 v69, 0xbfb8aa3b, v57
	v_rcp_f32_e32 v67, v67
	v_exp_f32_e32 v68, v68
	v_exp_f32_e32 v69, v69
	v_pk_mul_f32 v[48:49], v[48:49], v[154:155] op_sel_hi:[1,0]
	v_pk_mul_f32 v[60:61], v[60:61], v[66:67]
	v_add_f32_e32 v68, 1.0, v68
	v_add_f32_e32 v69, 1.0, v69
	v_pk_mul_f32 v[52:53], v[52:53], v[60:61]
	v_pk_mul_f32 v[60:61], v[62:63], v[154:155] op_sel_hi:[1,0]
	v_rcp_f32_e32 v68, v68
	v_rcp_f32_e32 v69, v69
	v_mul_f32_e32 v62, 0xbfb8aa3b, v60
	v_mul_f32_e32 v63, 0xbfb8aa3b, v61
	v_exp_f32_e32 v62, v62
	v_exp_f32_e32 v63, v63
	v_pk_mul_f32 v[56:57], v[56:57], v[68:69]
	v_pk_mul_f32 v[58:59], v[58:59], v[154:155] op_sel_hi:[1,0]
	v_pk_mul_f32 v[56:57], v[48:49], v[56:57]
	v_add_f32_e32 v48, 1.0, v62
	v_add_f32_e32 v49, 1.0, v63
	v_mul_f32_e32 v62, 0xbfb8aa3b, v58
	v_mul_f32_e32 v63, 0xbfb8aa3b, v59
	v_exp_f32_e32 v62, v62
	v_exp_f32_e32 v63, v63
	v_rcp_f32_e32 v48, v48
	v_rcp_f32_e32 v49, v49
	v_add_f32_e32 v62, 1.0, v62
	v_add_f32_e32 v63, 1.0, v63
	v_rcp_f32_e32 v62, v62
	v_rcp_f32_e32 v63, v63
	v_pk_mul_f32 v[48:49], v[60:61], v[48:49]
	v_pk_mul_f32 v[54:55], v[54:55], v[154:155] op_sel_hi:[1,0]
	v_add_u32_e32 v64, 0x80, v146
	v_pk_mul_f32 v[54:55], v[54:55], v[48:49]
	v_pk_mul_f32 v[48:49], v[58:59], v[62:63]
	v_pk_mul_f32 v[50:51], v[50:51], v[154:155] op_sel_hi:[1,0]
	v_mad_i64_i32 v[64:65], s[36:37], v64, s63, v[150:151]
	v_pk_mul_f32 v[58:59], v[50:51], v[48:49]
	v_lshl_add_u64 v[60:61], v[64:65], 0, v[112:113]
	v_cvt_pk_bf16_f32 v48, v52, v53
	v_cvt_pk_bf16_f32 v49, v54, v55
	v_cvt_pk_bf16_f32 v50, v56, v57
	v_cvt_pk_bf16_f32 v51, v58, v59
	v_pk_mul_f32 v[44:45], v[44:45], v[152:153] op_sel_hi:[1,0]
	global_store_dwordx4 v[60:61], v[48:51], off
	v_pk_mul_f32 v[40:41], v[40:41], v[152:153] op_sel_hi:[1,0]
	v_pk_mul_f32 v[36:37], v[36:37], v[152:153] op_sel_hi:[1,0]
	v_mul_f32_e32 v49, 0xbfb8aa3b, v44
	v_exp_f32_e32 v50, v49
	v_mul_f32_e32 v49, 0xbfb8aa3b, v45
	v_exp_f32_e32 v51, v49
	v_mul_f32_e32 v52, 0xbfb8aa3b, v40
	v_add_f32_e32 v50, 1.0, v50
	v_rcp_f32_e32 v50, v50
	v_add_f32_e32 v51, 1.0, v51
	v_mul_f32_e32 v53, 0xbfb8aa3b, v41
; #define PG8_WAIT_V(n) asm volatile("s_waitcnt vmcnt(" #n ")" ::: "memory")
; #define PG8_BAR __builtin_amdgcn_s_barrier()
; __device__ __forceinline__ unsigned pk2(float lo, float hi) { bf16x2_t r = __builtin_convertvector((f32x2_t){lo, hi}, bf16x2_t); return __builtin_bit_cast(unsigned, r); }
; __device__ __forceinline__ float sigmoid_fast(float x) { return __builtin_amdgcn_rcpf(1.0f + __builtin_amdgcn_exp2f(-1.44269504089f * x)); }
;     ...
;         if (!has_next) break;
;         if constexpr (PEEL) { PG8_WAIT_V(8); }
; #pragma unroll
;         for (int a = 0; a < 2; ++a)
; #pragma unroll
;             for (int b = 0; b < 2; ++b)
; #pragma unroll
;                 for (int m = 0; m < 4; ++m)
; #pragma unroll
;                     for (int n = 0; n < 2; ++n) acc[a][b][m][n] = (f32x4){0.f, 0.f, 0.f, 0.f};
;         cur = nxt; cA = nA; cB = nB; ck = nk; ++ui;
;         if constexpr (ALIGN_EPI) { if (wr == 1) PG8_BAR; }
;     __device__ __forceinline__ void operator()(const pg8::f32x4 (&acc)[2][2][4][2], const pg8::Unit& u, int wr, int wc, int fr, int fq) const {
;     ...
;                 const float rv = rvs[ai][m];
;                 bf16* p = O + (size_t)(row0 + ai * 128 + m * 16) * FF + col0;
;                 const pg8::f32x4 g0 = acc[ai][0][m][0] * rv, g1 = acc[ai][0][m][1] * rv, u0 = acc[ai][1][m][0] * rv, u1 = acc[ai][1][m][1] * rv;
;                 float r[8];
; #pragma unroll
;                 for (int j = 0; j < 4; ++j) { r[j] = g0[j] * sigmoid_fast(g0[j]) * u0[j]; r[4 + j] = g1[j] * sigmoid_fast(g1[j]) * u1[j]; }
;                 v4u w; w.x = pk2(r[0], r[1]); w.y = pk2(r[2], r[3]); w.z = pk2(r[4], r[5]); w.w = pk2(r[6], r[7]);
;                 __builtin_nontemporal_store(w, (v4u*)p);
;             }
	v_rcp_f32_e32 v51, v51
	v_exp_f32_e32 v52, v52
	v_exp_f32_e32 v53, v53
	v_pk_mul_f32 v[32:33], v[32:33], v[152:153] op_sel_hi:[1,0]
	v_pk_mul_f32 v[44:45], v[44:45], v[50:51]
	v_add_f32_e32 v52, 1.0, v52
	v_add_f32_e32 v53, 1.0, v53
	v_pk_mul_f32 v[36:37], v[36:37], v[44:45]
	v_pk_mul_f32 v[44:45], v[46:47], v[152:153] op_sel_hi:[1,0]
	v_rcp_f32_e32 v52, v52
	v_rcp_f32_e32 v53, v53
	v_mul_f32_e32 v46, 0xbfb8aa3b, v44
	v_mul_f32_e32 v47, 0xbfb8aa3b, v45
	v_exp_f32_e32 v46, v46
	v_exp_f32_e32 v47, v47
	v_pk_mul_f32 v[40:41], v[40:41], v[52:53]
	v_pk_mul_f32 v[42:43], v[42:43], v[152:153] op_sel_hi:[1,0]
	v_pk_mul_f32 v[40:41], v[32:33], v[40:41]
	v_add_f32_e32 v32, 1.0, v46
	v_add_f32_e32 v33, 1.0, v47
	v_mul_f32_e32 v46, 0xbfb8aa3b, v42
	v_mul_f32_e32 v47, 0xbfb8aa3b, v43
	v_exp_f32_e32 v46, v46
	v_exp_f32_e32 v47, v47
	v_rcp_f32_e32 v32, v32
	v_rcp_f32_e32 v33, v33
	v_add_f32_e32 v46, 1.0, v46
	v_add_f32_e32 v47, 1.0, v47
	v_rcp_f32_e32 v46, v46
	v_rcp_f32_e32 v47, v47
	v_pk_mul_f32 v[32:33], v[44:45], v[32:33]
	v_pk_mul_f32 v[38:39], v[38:39], v[152:153] op_sel_hi:[1,0]
	v_add_u32_e32 v48, 0x90, v146
	v_pk_mul_f32 v[38:39], v[38:39], v[32:33]
	v_pk_mul_f32 v[32:33], v[42:43], v[46:47]
	v_pk_mul_f32 v[34:35], v[34:35], v[152:153] op_sel_hi:[1,0]
	v_mad_i64_i32 v[48:49], s[36:37], v48, s63, v[150:151]
	v_pk_mul_f32 v[42:43], v[34:35], v[32:33]
	v_lshl_add_u64 v[44:45], v[48:49], 0, v[112:113]
	v_cvt_pk_bf16_f32 v32, v36, v37
	v_cvt_pk_bf16_f32 v33, v38, v39
	v_cvt_pk_bf16_f32 v34, v40, v41
	v_cvt_pk_bf16_f32 v35, v42, v43
	v_pk_mul_f32 v[28:29], v[28:29], v[148:149] op_sel_hi:[1,0]
	global_store_dwordx4 v[44:45], v[32:35], off
	v_pk_mul_f32 v[24:25], v[24:25], v[148:149] op_sel_hi:[1,0]
	v_pk_mul_f32 v[20:21], v[20:21], v[148:149] op_sel_hi:[1,0]
	v_mul_f32_e32 v33, 0xbfb8aa3b, v28
	v_exp_f32_e32 v34, v33
	v_mul_f32_e32 v33, 0xbfb8aa3b, v29
	v_exp_f32_e32 v35, v33
	v_mul_f32_e32 v36, 0xbfb8aa3b, v24
	v_add_f32_e32 v34, 1.0, v34
	v_rcp_f32_e32 v34, v34
	v_add_f32_e32 v35, 1.0, v35
	v_mul_f32_e32 v37, 0xbfb8aa3b, v25
	v_rcp_f32_e32 v35, v35
	v_exp_f32_e32 v36, v36
	v_exp_f32_e32 v37, v37
	v_pk_mul_f32 v[16:17], v[16:17], v[148:149] op_sel_hi:[1,0]
	v_pk_mul_f32 v[28:29], v[28:29], v[34:35]
	v_add_f32_e32 v36, 1.0, v36
	v_add_f32_e32 v37, 1.0, v37
	v_pk_mul_f32 v[20:21], v[20:21], v[28:29]
	v_pk_mul_f32 v[28:29], v[30:31], v[148:149] op_sel_hi:[1,0]
	v_rcp_f32_e32 v36, v36
	v_rcp_f32_e32 v37, v37
	v_mul_f32_e32 v30, 0xbfb8aa3b, v28
	v_mul_f32_e32 v31, 0xbfb8aa3b, v29
	v_exp_f32_e32 v30, v30
	v_exp_f32_e32 v31, v31
	v_pk_mul_f32 v[24:25], v[24:25], v[36:37]
	v_pk_mul_f32 v[26:27], v[26:27], v[148:149] op_sel_hi:[1,0]
	v_pk_mul_f32 v[24:25], v[16:17], v[24:25]
	v_add_f32_e32 v16, 1.0, v30
	v_add_f32_e32 v17, 1.0, v31
	v_mul_f32_e32 v30, 0xbfb8aa3b, v26
	v_mul_f32_e32 v31, 0xbfb8aa3b, v27
	v_exp_f32_e32 v30, v30
	v_exp_f32_e32 v31, v31
	v_rcp_f32_e32 v16, v16
	v_rcp_f32_e32 v17, v17
	v_add_f32_e32 v30, 1.0, v30
	v_add_f32_e32 v31, 1.0, v31
	v_rcp_f32_e32 v30, v30
	v_rcp_f32_e32 v31, v31
	v_pk_mul_f32 v[16:17], v[28:29], v[16:17]
	v_pk_mul_f32 v[22:23], v[22:23], v[148:149] op_sel_hi:[1,0]
	v_add_u32_e32 v32, 0xa0, v146
	v_pk_mul_f32 v[22:23], v[22:23], v[16:17]
	v_pk_mul_f32 v[16:17], v[26:27], v[30:31]
	v_pk_mul_f32 v[18:19], v[18:19], v[148:149] op_sel_hi:[1,0]
	v_mad_i64_i32 v[32:33], s[36:37], v32, s63, v[150:151]
	v_pk_mul_f32 v[26:27], v[18:19], v[16:17]
	v_lshl_add_u64 v[28:29], v[32:33], 0, v[112:113]
	v_cvt_pk_bf16_f32 v16, v20, v21
	v_cvt_pk_bf16_f32 v17, v22, v23
	v_cvt_pk_bf16_f32 v18, v24, v25
	v_cvt_pk_bf16_f32 v19, v26, v27
	v_pk_mul_f32 v[12:13], v[12:13], v[144:145] op_sel_hi:[1,0]
	global_store_dwordx4 v[28:29], v[16:19], off
	v_pk_mul_f32 v[8:9], v[8:9], v[144:145] op_sel_hi:[1,0]
	v_pk_mul_f32 v[4:5], v[4:5], v[144:145] op_sel_hi:[1,0]
	v_mul_f32_e32 v17, 0xbfb8aa3b, v12
	v_exp_f32_e32 v18, v17
	v_mul_f32_e32 v17, 0xbfb8aa3b, v13
	v_exp_f32_e32 v19, v17
	v_mul_f32_e32 v20, 0xbfb8aa3b, v8
	v_add_f32_e32 v18, 1.0, v18
	v_rcp_f32_e32 v18, v18
	v_add_f32_e32 v19, 1.0, v19
	v_mul_f32_e32 v21, 0xbfb8aa3b, v9
	v_rcp_f32_e32 v19, v19
	v_exp_f32_e32 v20, v20
	v_exp_f32_e32 v21, v21
	v_pk_mul_f32 v[0:1], v[0:1], v[144:145] op_sel_hi:[1,0]
	v_pk_mul_f32 v[12:13], v[12:13], v[18:19]
	v_add_f32_e32 v20, 1.0, v20
	v_add_f32_e32 v21, 1.0, v21
	v_pk_mul_f32 v[4:5], v[4:5], v[12:13]
	v_pk_mul_f32 v[12:13], v[14:15], v[144:145] op_sel_hi:[1,0]
	v_rcp_f32_e32 v20, v20
	v_rcp_f32_e32 v21, v21
	v_mul_f32_e32 v14, 0xbfb8aa3b, v12
	v_mul_f32_e32 v15, 0xbfb8aa3b, v13
	v_exp_f32_e32 v14, v14
	v_exp_f32_e32 v15, v15
	v_pk_mul_f32 v[8:9], v[8:9], v[20:21]
	v_pk_mul_f32 v[10:11], v[10:11], v[144:145] op_sel_hi:[1,0]
	v_pk_mul_f32 v[8:9], v[0:1], v[8:9]
	v_add_f32_e32 v0, 1.0, v14
	v_add_f32_e32 v1, 1.0, v15
	v_mul_f32_e32 v14, 0xbfb8aa3b, v10
	v_mul_f32_e32 v15, 0xbfb8aa3b, v11
	v_exp_f32_e32 v14, v14
	v_exp_f32_e32 v15, v15
	v_rcp_f32_e32 v0, v0
	v_rcp_f32_e32 v1, v1
	v_add_f32_e32 v14, 1.0, v14
	v_add_f32_e32 v15, 1.0, v15
	v_rcp_f32_e32 v14, v14
	v_rcp_f32_e32 v15, v15
	v_pk_mul_f32 v[0:1], v[12:13], v[0:1]
	v_pk_mul_f32 v[6:7], v[6:7], v[144:145] op_sel_hi:[1,0]
	v_add_u32_e32 v16, 0xb0, v146
	v_pk_mul_f32 v[6:7], v[6:7], v[0:1]
	v_pk_mul_f32 v[0:1], v[10:11], v[14:15]
	v_pk_mul_f32 v[2:3], v[2:3], v[144:145] op_sel_hi:[1,0]
	v_mad_i64_i32 v[16:17], s[36:37], v16, s63, v[150:151]
	v_pk_mul_f32 v[10:11], v[2:3], v[0:1]
	v_lshl_add_u64 v[12:13], v[16:17], 0, v[112:113]
	v_cvt_pk_bf16_f32 v0, v4, v5
	v_cvt_pk_bf16_f32 v1, v6, v7
	v_cvt_pk_bf16_f32 v2, v8, v9
	v_cvt_pk_bf16_f32 v3, v10, v11
	s_andn2_b64 vcc, exec, s[0:1]
	s_mov_b64 s[0:1], -1
	global_store_dwordx4 v[12:13], v[0:3], off
	s_cbranch_vccnz .LBB0_240
	s_andn2_b64 vcc, exec, s[4:5]
	s_cbranch_vccnz .LBB0_239
	s_barrier
	s_branch .LBB0_239

; __device__ __forceinline__ unsigned pk2(float lo, float hi) { bf16x2_t r = __builtin_convertvector((f32x2_t){lo, hi}, bf16x2_t); return __builtin_bit_cast(unsigned, r); }
; __device__ __forceinline__ float sigmoid_fast(float x) { return __builtin_amdgcn_rcpf(1.0f + __builtin_amdgcn_exp2f(-1.44269504089f * x)); }
;     __device__ __forceinline__ void operator()(const pg8::f32x4 (&acc)[2][2][4][2], const pg8::Unit& u, int wr, int wc, int fr, int fq) const {
;         const int row0 = u.pm * 256 + wr * 64 + fr, col0 = u.pn * 128 + wc * 32 + 8 * fq;
;         float rvs[2][4]; rs_rows(lds, rs, u.pm, wr, fr, rvs);
; #pragma unroll
;         for (int ai = 0; ai < 2; ++ai)
; #pragma unroll
;             for (int m = 0; m < 4; ++m) {
;                 const float rv = rvs[ai][m];
;                 bf16* p = O + (size_t)(row0 + ai * 128 + m * 16) * FF + col0;
;                 const pg8::f32x4 g0 = acc[ai][0][m][0] * rv, g1 = acc[ai][0][m][1] * rv, u0 = acc[ai][1][m][0] * rv, u1 = acc[ai][1][m][1] * rv;
;                 float r[8];
; #pragma unroll
;                 for (int j = 0; j < 4; ++j) { r[j] = g0[j] * sigmoid_fast(g0[j]) * u0[j]; r[4 + j] = g1[j] * sigmoid_fast(g1[j]) * u1[j]; }
;                 v4u w; w.x = pk2(r[0], r[1]); w.y = pk2(r[2], r[3]); w.z = pk2(r[4], r[5]); w.w = pk2(r[6], r[7]);
;                 __builtin_nontemporal_store(w, (v4u*)p);
;             }
.LBB0_1080:
	s_waitcnt vmcnt(0)
	v_pk_mul_f32 v[124:125], v[124:125], v[162:163] op_sel_hi:[1,0]
	v_mov_b64_e32 v[150:151], s[16:17]
	v_mul_f32_e32 v147, 0xbfb8aa3b, v124
	v_exp_f32_e32 v147, v147
	v_mul_f32_e32 v149, 0xbfb8aa3b, v125
	v_exp_f32_e32 v149, v149
	v_mad_u64_u32 v[172:173], s[26:27], v164, s57, v[150:151]
	v_mov_b32_e32 v164, v173
	v_mad_u64_u32 v[164:165], s[26:27], v165, s57, v[164:165]
	v_add_f32_e32 v147, 1.0, v147
	v_pk_mul_f32 v[120:121], v[120:121], v[162:163] op_sel_hi:[1,0]
	v_mov_b32_e32 v173, v164
	v_rcp_f32_e32 v164, v147
	v_add_f32_e32 v147, 1.0, v149
	v_mul_f32_e32 v149, 0xbfb8aa3b, v120
	v_exp_f32_e32 v149, v149
	v_mul_f32_e32 v155, 0xbfb8aa3b, v121
	v_rcp_f32_e32 v165, v147
	v_exp_f32_e32 v155, v155
	v_add_f32_e32 v147, 1.0, v149
	v_pk_mul_f32 v[116:117], v[116:117], v[162:163] op_sel_hi:[1,0]
	v_pk_mul_f32 v[124:125], v[124:125], v[164:165]
	v_rcp_f32_e32 v174, v147
	v_add_f32_e32 v147, 1.0, v155
	v_pk_mul_f32 v[116:117], v[116:117], v[124:125]
	v_pk_mul_f32 v[124:125], v[126:127], v[162:163] op_sel_hi:[1,0]
	v_rcp_f32_e32 v175, v147
	v_mul_f32_e32 v126, 0xbfb8aa3b, v124
	v_mul_f32_e32 v127, 0xbfb8aa3b, v125
	v_exp_f32_e32 v126, v126
	v_exp_f32_e32 v127, v127
	v_pk_mul_f32 v[120:121], v[120:121], v[174:175]
	v_pk_mul_f32 v[112:113], v[112:113], v[162:163] op_sel_hi:[1,0]
	v_pk_mul_f32 v[122:123], v[122:123], v[162:163] op_sel_hi:[1,0]
	v_pk_mul_f32 v[120:121], v[112:113], v[120:121]
	v_add_f32_e32 v112, 1.0, v126
	v_add_f32_e32 v113, 1.0, v127
	v_mul_f32_e32 v126, 0xbfb8aa3b, v122
	v_mul_f32_e32 v127, 0xbfb8aa3b, v123
	v_exp_f32_e32 v126, v126
	v_exp_f32_e32 v127, v127
	v_rcp_f32_e32 v112, v112
	v_rcp_f32_e32 v113, v113
	v_add_f32_e32 v126, 1.0, v126
	v_add_f32_e32 v127, 1.0, v127
	v_rcp_f32_e32 v126, v126
	v_rcp_f32_e32 v127, v127
	v_lshl_or_b32 v170, s58, 7, v161
	v_pk_mul_f32 v[112:113], v[124:125], v[112:113]
	v_pk_mul_f32 v[118:119], v[118:119], v[162:163] op_sel_hi:[1,0]
	v_ashrrev_i32_e32 v171, 31, v170
	v_pk_mul_f32 v[118:119], v[118:119], v[112:113]
	v_pk_mul_f32 v[112:113], v[122:123], v[126:127]
	v_pk_mul_f32 v[114:115], v[114:115], v[162:163] op_sel_hi:[1,0]
	v_pk_mul_f32 v[108:109], v[108:109], v[160:161] op_sel_hi:[1,0]
	v_pk_mul_f32 v[122:123], v[114:115], v[112:113]
	v_lshlrev_b64 v[112:113], 1, v[170:171]
	v_lshl_add_u64 v[124:125], v[172:173], 0, v[112:113]
	v_cvt_pk_bf16_f32 v114, v116, v117
	v_cvt_pk_bf16_f32 v115, v118, v119
	v_cvt_pk_bf16_f32 v116, v120, v121
	v_cvt_pk_bf16_f32 v117, v122, v123
	global_store_dwordx4 v[124:125], v[114:117], off
	v_pk_mul_f32 v[104:105], v[104:105], v[160:161] op_sel_hi:[1,0]
	v_pk_mul_f32 v[100:101], v[100:101], v[160:161] op_sel_hi:[1,0]
	v_mul_f32_e32 v115, 0xbfb8aa3b, v108
	v_exp_f32_e32 v116, v115
	v_mul_f32_e32 v115, 0xbfb8aa3b, v109
	v_exp_f32_e32 v117, v115
	v_mul_f32_e32 v118, 0xbfb8aa3b, v104
	v_add_f32_e32 v116, 1.0, v116
	v_rcp_f32_e32 v116, v116
	v_add_f32_e32 v117, 1.0, v117
	v_mul_f32_e32 v119, 0xbfb8aa3b, v105
	v_rcp_f32_e32 v117, v117
	v_exp_f32_e32 v118, v118
	v_exp_f32_e32 v119, v119
	v_pk_mul_f32 v[96:97], v[96:97], v[160:161] op_sel_hi:[1,0]
	v_pk_mul_f32 v[108:109], v[108:109], v[116:117]
	v_add_f32_e32 v118, 1.0, v118
	v_add_f32_e32 v119, 1.0, v119
	v_pk_mul_f32 v[100:101], v[100:101], v[108:109]
	v_pk_mul_f32 v[108:109], v[110:111], v[160:161] op_sel_hi:[1,0]
	v_rcp_f32_e32 v118, v118
	v_rcp_f32_e32 v119, v119
	v_mul_f32_e32 v110, 0xbfb8aa3b, v108
	v_mul_f32_e32 v111, 0xbfb8aa3b, v109
	v_exp_f32_e32 v110, v110
	v_exp_f32_e32 v111, v111
	v_pk_mul_f32 v[104:105], v[104:105], v[118:119]
	v_pk_mul_f32 v[106:107], v[106:107], v[160:161] op_sel_hi:[1,0]
	v_pk_mul_f32 v[104:105], v[96:97], v[104:105]
	v_add_f32_e32 v96, 1.0, v110
	v_add_f32_e32 v97, 1.0, v111
	v_mul_f32_e32 v110, 0xbfb8aa3b, v106
	v_mul_f32_e32 v111, 0xbfb8aa3b, v107
	v_exp_f32_e32 v110, v110
	v_exp_f32_e32 v111, v111
	v_rcp_f32_e32 v96, v96
	v_rcp_f32_e32 v97, v97
	v_add_f32_e32 v110, 1.0, v110
	v_add_f32_e32 v111, 1.0, v111
	v_rcp_f32_e32 v110, v110
	v_rcp_f32_e32 v111, v111
	v_pk_mul_f32 v[96:97], v[108:109], v[96:97]
	v_pk_mul_f32 v[102:103], v[102:103], v[160:161] op_sel_hi:[1,0]
	v_or_b32_e32 v114, 16, v146
	v_pk_mul_f32 v[102:103], v[102:103], v[96:97]
	v_pk_mul_f32 v[96:97], v[106:107], v[110:111]
	v_pk_mul_f32 v[98:99], v[98:99], v[160:161] op_sel_hi:[1,0]
	v_mad_i64_i32 v[114:115], s[26:27], v114, s57, v[150:151]
	v_pk_mul_f32 v[106:107], v[98:99], v[96:97]
	v_lshl_add_u64 v[108:109], v[114:115], 0, v[112:113]
	v_cvt_pk_bf16_f32 v96, v100, v101
	v_cvt_pk_bf16_f32 v97, v102, v103
	v_cvt_pk_bf16_f32 v98, v104, v105
	v_cvt_pk_bf16_f32 v99, v106, v107
	v_pk_mul_f32 v[92:93], v[92:93], v[158:159] op_sel_hi:[1,0]
	global_store_dwordx4 v[108:109], v[96:99], off
	v_pk_mul_f32 v[88:89], v[88:89], v[158:159] op_sel_hi:[1,0]
	v_pk_mul_f32 v[84:85], v[84:85], v[158:159] op_sel_hi:[1,0]
	v_mul_f32_e32 v97, 0xbfb8aa3b, v92
	v_exp_f32_e32 v98, v97
	v_mul_f32_e32 v97, 0xbfb8aa3b, v93
	v_exp_f32_e32 v99, v97
	v_mul_f32_e32 v100, 0xbfb8aa3b, v88
	v_add_f32_e32 v98, 1.0, v98
	v_rcp_f32_e32 v98, v98
	v_add_f32_e32 v99, 1.0, v99
	v_mul_f32_e32 v101, 0xbfb8aa3b, v89
	v_rcp_f32_e32 v99, v99
	v_exp_f32_e32 v100, v100
	v_exp_f32_e32 v101, v101
	v_pk_mul_f32 v[80:81], v[80:81], v[158:159] op_sel_hi:[1,0]
	v_pk_mul_f32 v[92:93], v[92:93], v[98:99]
	v_add_f32_e32 v100, 1.0, v100
	v_add_f32_e32 v101, 1.0, v101
	v_pk_mul_f32 v[84:85], v[84:85], v[92:93]
	v_pk_mul_f32 v[92:93], v[94:95], v[158:159] op_sel_hi:[1,0]
	v_rcp_f32_e32 v100, v100
	v_rcp_f32_e32 v101, v101
	v_mul_f32_e32 v94, 0xbfb8aa3b, v92
	v_mul_f32_e32 v95, 0xbfb8aa3b, v93
	v_exp_f32_e32 v94, v94
	v_exp_f32_e32 v95, v95
; __device__ __forceinline__ unsigned pk2(float lo, float hi) { bf16x2_t r = __builtin_convertvector((f32x2_t){lo, hi}, bf16x2_t); return __builtin_bit_cast(unsigned, r); }
; __device__ __forceinline__ float sigmoid_fast(float x) { return __builtin_amdgcn_rcpf(1.0f + __builtin_amdgcn_exp2f(-1.44269504089f * x)); }
;     __device__ __forceinline__ void operator()(const pg8::f32x4 (&acc)[2][2][4][2], const pg8::Unit& u, int wr, int wc, int fr, int fq) const {
;     ...
;                 const float rv = rvs[ai][m];
;                 bf16* p = O + (size_t)(row0 + ai * 128 + m * 16) * FF + col0;
;                 const pg8::f32x4 g0 = acc[ai][0][m][0] * rv, g1 = acc[ai][0][m][1] * rv, u0 = acc[ai][1][m][0] * rv, u1 = acc[ai][1][m][1] * rv;
;                 float r[8];
; #pragma unroll
;                 for (int j = 0; j < 4; ++j) { r[j] = g0[j] * sigmoid_fast(g0[j]) * u0[j]; r[4 + j] = g1[j] * sigmoid_fast(g1[j]) * u1[j]; }
;                 v4u w; w.x = pk2(r[0], r[1]); w.y = pk2(r[2], r[3]); w.z = pk2(r[4], r[5]); w.w = pk2(r[6], r[7]);
;                 __builtin_nontemporal_store(w, (v4u*)p);
	v_pk_mul_f32 v[88:89], v[88:89], v[100:101]
	v_pk_mul_f32 v[90:91], v[90:91], v[158:159] op_sel_hi:[1,0]
	v_pk_mul_f32 v[88:89], v[80:81], v[88:89]
	v_add_f32_e32 v80, 1.0, v94
	v_add_f32_e32 v81, 1.0, v95
	v_mul_f32_e32 v94, 0xbfb8aa3b, v90
	v_mul_f32_e32 v95, 0xbfb8aa3b, v91
	v_exp_f32_e32 v94, v94
	v_exp_f32_e32 v95, v95
	v_rcp_f32_e32 v80, v80
	v_rcp_f32_e32 v81, v81
	v_add_f32_e32 v94, 1.0, v94
	v_add_f32_e32 v95, 1.0, v95
	v_rcp_f32_e32 v94, v94
	v_rcp_f32_e32 v95, v95
	v_pk_mul_f32 v[80:81], v[92:93], v[80:81]
	v_pk_mul_f32 v[86:87], v[86:87], v[158:159] op_sel_hi:[1,0]
	v_or_b32_e32 v96, 32, v146
	v_pk_mul_f32 v[86:87], v[86:87], v[80:81]
	v_pk_mul_f32 v[80:81], v[90:91], v[94:95]
	v_pk_mul_f32 v[82:83], v[82:83], v[158:159] op_sel_hi:[1,0]
	v_mad_i64_i32 v[96:97], s[26:27], v96, s57, v[150:151]
	v_pk_mul_f32 v[90:91], v[82:83], v[80:81]
	v_lshl_add_u64 v[92:93], v[96:97], 0, v[112:113]
	v_cvt_pk_bf16_f32 v80, v84, v85
	v_cvt_pk_bf16_f32 v81, v86, v87
	v_cvt_pk_bf16_f32 v82, v88, v89
	v_cvt_pk_bf16_f32 v83, v90, v91
	v_pk_mul_f32 v[76:77], v[76:77], v[156:157] op_sel_hi:[1,0]
	global_store_dwordx4 v[92:93], v[80:83], off
	v_pk_mul_f32 v[72:73], v[72:73], v[156:157] op_sel_hi:[1,0]
	v_pk_mul_f32 v[68:69], v[68:69], v[156:157] op_sel_hi:[1,0]
	v_mul_f32_e32 v81, 0xbfb8aa3b, v76
	v_exp_f32_e32 v82, v81
	v_mul_f32_e32 v81, 0xbfb8aa3b, v77
	v_exp_f32_e32 v83, v81
	v_mul_f32_e32 v84, 0xbfb8aa3b, v72
	v_add_f32_e32 v82, 1.0, v82
	v_rcp_f32_e32 v82, v82
	v_add_f32_e32 v83, 1.0, v83
	v_mul_f32_e32 v85, 0xbfb8aa3b, v73
	v_rcp_f32_e32 v83, v83
	v_exp_f32_e32 v84, v84
	v_exp_f32_e32 v85, v85
	v_pk_mul_f32 v[64:65], v[64:65], v[156:157] op_sel_hi:[1,0]
	v_pk_mul_f32 v[76:77], v[76:77], v[82:83]
	v_add_f32_e32 v84, 1.0, v84
	v_add_f32_e32 v85, 1.0, v85
	v_pk_mul_f32 v[68:69], v[68:69], v[76:77]
	v_pk_mul_f32 v[76:77], v[78:79], v[156:157] op_sel_hi:[1,0]
	v_rcp_f32_e32 v84, v84
	v_rcp_f32_e32 v85, v85
	v_mul_f32_e32 v78, 0xbfb8aa3b, v76
	v_mul_f32_e32 v79, 0xbfb8aa3b, v77
	v_exp_f32_e32 v78, v78
	v_exp_f32_e32 v79, v79
	v_pk_mul_f32 v[72:73], v[72:73], v[84:85]
	v_pk_mul_f32 v[74:75], v[74:75], v[156:157] op_sel_hi:[1,0]
	v_pk_mul_f32 v[72:73], v[64:65], v[72:73]
	v_add_f32_e32 v64, 1.0, v78
	v_add_f32_e32 v65, 1.0, v79
	v_mul_f32_e32 v78, 0xbfb8aa3b, v74
	v_mul_f32_e32 v79, 0xbfb8aa3b, v75
	v_exp_f32_e32 v78, v78
	v_exp_f32_e32 v79, v79
	v_rcp_f32_e32 v64, v64
	v_rcp_f32_e32 v65, v65
	v_add_f32_e32 v78, 1.0, v78
	v_add_f32_e32 v79, 1.0, v79
	v_rcp_f32_e32 v78, v78
	v_rcp_f32_e32 v79, v79
	v_pk_mul_f32 v[64:65], v[76:77], v[64:65]
	v_pk_mul_f32 v[70:71], v[70:71], v[156:157] op_sel_hi:[1,0]
	v_or_b32_e32 v80, 48, v146
	v_pk_mul_f32 v[70:71], v[70:71], v[64:65]
	v_pk_mul_f32 v[64:65], v[74:75], v[78:79]
	v_pk_mul_f32 v[66:67], v[66:67], v[156:157] op_sel_hi:[1,0]
	v_mad_i64_i32 v[80:81], s[26:27], v80, s57, v[150:151]
	v_pk_mul_f32 v[74:75], v[66:67], v[64:65]
	v_lshl_add_u64 v[76:77], v[80:81], 0, v[112:113]
	v_cvt_pk_bf16_f32 v64, v68, v69
	v_cvt_pk_bf16_f32 v65, v70, v71
	v_cvt_pk_bf16_f32 v66, v72, v73
	v_cvt_pk_bf16_f32 v67, v74, v75
	v_pk_mul_f32 v[60:61], v[60:61], v[154:155] op_sel_hi:[1,0]
	global_store_dwordx4 v[76:77], v[64:67], off
	v_pk_mul_f32 v[56:57], v[56:57], v[154:155] op_sel_hi:[1,0]
	v_pk_mul_f32 v[52:53], v[52:53], v[154:155] op_sel_hi:[1,0]
	v_mul_f32_e32 v65, 0xbfb8aa3b, v60
	v_exp_f32_e32 v66, v65
	v_mul_f32_e32 v65, 0xbfb8aa3b, v61
	v_exp_f32_e32 v67, v65
	v_mul_f32_e32 v68, 0xbfb8aa3b, v56
	v_add_f32_e32 v66, 1.0, v66
	v_rcp_f32_e32 v66, v66
	v_add_f32_e32 v67, 1.0, v67
	v_mul_f32_e32 v69, 0xbfb8aa3b, v57
	v_rcp_f32_e32 v67, v67
	v_exp_f32_e32 v68, v68
	v_exp_f32_e32 v69, v69
	v_pk_mul_f32 v[48:49], v[48:49], v[154:155] op_sel_hi:[1,0]
	v_pk_mul_f32 v[60:61], v[60:61], v[66:67]
	v_add_f32_e32 v68, 1.0, v68
	v_add_f32_e32 v69, 1.0, v69
	v_pk_mul_f32 v[52:53], v[52:53], v[60:61]
	v_pk_mul_f32 v[60:61], v[62:63], v[154:155] op_sel_hi:[1,0]
	v_rcp_f32_e32 v68, v68
	v_rcp_f32_e32 v69, v69
	v_mul_f32_e32 v62, 0xbfb8aa3b, v60
	v_mul_f32_e32 v63, 0xbfb8aa3b, v61
	v_exp_f32_e32 v62, v62
	v_exp_f32_e32 v63, v63
	v_pk_mul_f32 v[56:57], v[56:57], v[68:69]
	v_pk_mul_f32 v[58:59], v[58:59], v[154:155] op_sel_hi:[1,0]
	v_pk_mul_f32 v[56:57], v[48:49], v[56:57]
	v_add_f32_e32 v48, 1.0, v62
	v_add_f32_e32 v49, 1.0, v63
	v_mul_f32_e32 v62, 0xbfb8aa3b, v58
	v_mul_f32_e32 v63, 0xbfb8aa3b, v59
	v_exp_f32_e32 v62, v62
	v_exp_f32_e32 v63, v63
	v_rcp_f32_e32 v48, v48
	v_rcp_f32_e32 v49, v49
	v_add_f32_e32 v62, 1.0, v62
	v_add_f32_e32 v63, 1.0, v63
	v_rcp_f32_e32 v62, v62
	v_rcp_f32_e32 v63, v63
	v_pk_mul_f32 v[48:49], v[60:61], v[48:49]
	v_pk_mul_f32 v[54:55], v[54:55], v[154:155] op_sel_hi:[1,0]
	v_add_u32_e32 v64, 0x80, v146
	v_pk_mul_f32 v[54:55], v[54:55], v[48:49]
	v_pk_mul_f32 v[48:49], v[58:59], v[62:63]
	v_pk_mul_f32 v[50:51], v[50:51], v[154:155] op_sel_hi:[1,0]
	v_mad_i64_i32 v[64:65], s[26:27], v64, s57, v[150:151]
	v_pk_mul_f32 v[58:59], v[50:51], v[48:49]
	v_lshl_add_u64 v[60:61], v[64:65], 0, v[112:113]
	v_cvt_pk_bf16_f32 v48, v52, v53
	v_cvt_pk_bf16_f32 v49, v54, v55
	v_cvt_pk_bf16_f32 v50, v56, v57
	v_cvt_pk_bf16_f32 v51, v58, v59
	v_pk_mul_f32 v[44:45], v[44:45], v[152:153] op_sel_hi:[1,0]
	global_store_dwordx4 v[60:61], v[48:51], off
	v_pk_mul_f32 v[40:41], v[40:41], v[152:153] op_sel_hi:[1,0]
	v_pk_mul_f32 v[36:37], v[36:37], v[152:153] op_sel_hi:[1,0]
	v_mul_f32_e32 v49, 0xbfb8aa3b, v44
	v_exp_f32_e32 v50, v49
	v_mul_f32_e32 v49, 0xbfb8aa3b, v45
	v_exp_f32_e32 v51, v49
	v_mul_f32_e32 v52, 0xbfb8aa3b, v40
	v_add_f32_e32 v50, 1.0, v50
	v_rcp_f32_e32 v50, v50
	v_add_f32_e32 v51, 1.0, v51
	v_mul_f32_e32 v53, 0xbfb8aa3b, v41
; #define PG8_WAIT_V(n) asm volatile("s_waitcnt vmcnt(" #n ")" ::: "memory")
; #define PG8_BAR __builtin_amdgcn_s_barrier()
; __device__ __forceinline__ unsigned pk2(float lo, float hi) { bf16x2_t r = __builtin_convertvector((f32x2_t){lo, hi}, bf16x2_t); return __builtin_bit_cast(unsigned, r); }
; __device__ __forceinline__ float sigmoid_fast(float x) { return __builtin_amdgcn_rcpf(1.0f + __builtin_amdgcn_exp2f(-1.44269504089f * x)); }
;     ...
;         if (!has_next) break;
;         if constexpr (PEEL) { PG8_WAIT_V(8); }
; #pragma unroll
;         for (int a = 0; a < 2; ++a)
; #pragma unroll
;             for (int b = 0; b < 2; ++b)
; #pragma unroll
;                 for (int m = 0; m < 4; ++m)
; #pragma unroll
;                     for (int n = 0; n < 2; ++n) acc[a][b][m][n] = (f32x4){0.f, 0.f, 0.f, 0.f};
;         cur = nxt; cA = nA; cB = nB; ck = nk; ++ui;
;         if constexpr (ALIGN_EPI) { if (wr == 1) PG8_BAR; }
;     __device__ __forceinline__ void operator()(const pg8::f32x4 (&acc)[2][2][4][2], const pg8::Unit& u, int wr, int wc, int fr, int fq) const {
;     ...
;                 const float rv = rvs[ai][m];
;                 bf16* p = O + (size_t)(row0 + ai * 128 + m * 16) * FF + col0;
;                 const pg8::f32x4 g0 = acc[ai][0][m][0] * rv, g1 = acc[ai][0][m][1] * rv, u0 = acc[ai][1][m][0] * rv, u1 = acc[ai][1][m][1] * rv;
;                 float r[8];
; #pragma unroll
;                 for (int j = 0; j < 4; ++j) { r[j] = g0[j] * sigmoid_fast(g0[j]) * u0[j]; r[4 + j] = g1[j] * sigmoid_fast(g1[j]) * u1[j]; }
;                 v4u w; w.x = pk2(r[0], r[1]); w.y = pk2(r[2], r[3]); w.z = pk2(r[4], r[5]); w.w = pk2(r[6], r[7]);
;                 __builtin_nontemporal_store(w, (v4u*)p);
;             }
	v_rcp_f32_e32 v51, v51
	v_exp_f32_e32 v52, v52
	v_exp_f32_e32 v53, v53
	v_pk_mul_f32 v[32:33], v[32:33], v[152:153] op_sel_hi:[1,0]
	v_pk_mul_f32 v[44:45], v[44:45], v[50:51]
	v_add_f32_e32 v52, 1.0, v52
	v_add_f32_e32 v53, 1.0, v53
	v_pk_mul_f32 v[36:37], v[36:37], v[44:45]
	v_pk_mul_f32 v[44:45], v[46:47], v[152:153] op_sel_hi:[1,0]
	v_rcp_f32_e32 v52, v52
	v_rcp_f32_e32 v53, v53
	v_mul_f32_e32 v46, 0xbfb8aa3b, v44
	v_mul_f32_e32 v47, 0xbfb8aa3b, v45
	v_exp_f32_e32 v46, v46
	v_exp_f32_e32 v47, v47
	v_pk_mul_f32 v[40:41], v[40:41], v[52:53]
	v_pk_mul_f32 v[42:43], v[42:43], v[152:153] op_sel_hi:[1,0]
	v_pk_mul_f32 v[40:41], v[32:33], v[40:41]
	v_add_f32_e32 v32, 1.0, v46
	v_add_f32_e32 v33, 1.0, v47
	v_mul_f32_e32 v46, 0xbfb8aa3b, v42
	v_mul_f32_e32 v47, 0xbfb8aa3b, v43
	v_exp_f32_e32 v46, v46
	v_exp_f32_e32 v47, v47
	v_rcp_f32_e32 v32, v32
	v_rcp_f32_e32 v33, v33
	v_add_f32_e32 v46, 1.0, v46
	v_add_f32_e32 v47, 1.0, v47
	v_rcp_f32_e32 v46, v46
	v_rcp_f32_e32 v47, v47
	v_pk_mul_f32 v[32:33], v[44:45], v[32:33]
	v_pk_mul_f32 v[38:39], v[38:39], v[152:153] op_sel_hi:[1,0]
	v_add_u32_e32 v48, 0x90, v146
	v_pk_mul_f32 v[38:39], v[38:39], v[32:33]
	v_pk_mul_f32 v[32:33], v[42:43], v[46:47]
	v_pk_mul_f32 v[34:35], v[34:35], v[152:153] op_sel_hi:[1,0]
	v_mad_i64_i32 v[48:49], s[26:27], v48, s57, v[150:151]
	v_pk_mul_f32 v[42:43], v[34:35], v[32:33]
	v_lshl_add_u64 v[44:45], v[48:49], 0, v[112:113]
	v_cvt_pk_bf16_f32 v32, v36, v37
	v_cvt_pk_bf16_f32 v33, v38, v39
	v_cvt_pk_bf16_f32 v34, v40, v41
	v_cvt_pk_bf16_f32 v35, v42, v43
	v_pk_mul_f32 v[28:29], v[28:29], v[148:149] op_sel_hi:[1,0]
	global_store_dwordx4 v[44:45], v[32:35], off
	v_pk_mul_f32 v[24:25], v[24:25], v[148:149] op_sel_hi:[1,0]
	v_pk_mul_f32 v[20:21], v[20:21], v[148:149] op_sel_hi:[1,0]
	v_mul_f32_e32 v33, 0xbfb8aa3b, v28
	v_exp_f32_e32 v34, v33
	v_mul_f32_e32 v33, 0xbfb8aa3b, v29
	v_exp_f32_e32 v35, v33
	v_mul_f32_e32 v36, 0xbfb8aa3b, v24
	v_add_f32_e32 v34, 1.0, v34
	v_rcp_f32_e32 v34, v34
	v_add_f32_e32 v35, 1.0, v35
	v_mul_f32_e32 v37, 0xbfb8aa3b, v25
	v_rcp_f32_e32 v35, v35
	v_exp_f32_e32 v36, v36
	v_exp_f32_e32 v37, v37
	v_pk_mul_f32 v[16:17], v[16:17], v[148:149] op_sel_hi:[1,0]
	v_pk_mul_f32 v[28:29], v[28:29], v[34:35]
	v_add_f32_e32 v36, 1.0, v36
	v_add_f32_e32 v37, 1.0, v37
	v_pk_mul_f32 v[20:21], v[20:21], v[28:29]
	v_pk_mul_f32 v[28:29], v[30:31], v[148:149] op_sel_hi:[1,0]
	v_rcp_f32_e32 v36, v36
	v_rcp_f32_e32 v37, v37
	v_mul_f32_e32 v30, 0xbfb8aa3b, v28
	v_mul_f32_e32 v31, 0xbfb8aa3b, v29
	v_exp_f32_e32 v30, v30
	v_exp_f32_e32 v31, v31
	v_pk_mul_f32 v[24:25], v[24:25], v[36:37]
	v_pk_mul_f32 v[26:27], v[26:27], v[148:149] op_sel_hi:[1,0]
	v_pk_mul_f32 v[24:25], v[16:17], v[24:25]
	v_add_f32_e32 v16, 1.0, v30
	v_add_f32_e32 v17, 1.0, v31
	v_mul_f32_e32 v30, 0xbfb8aa3b, v26
	v_mul_f32_e32 v31, 0xbfb8aa3b, v27
	v_exp_f32_e32 v30, v30
	v_exp_f32_e32 v31, v31
	v_rcp_f32_e32 v16, v16
	v_rcp_f32_e32 v17, v17
	v_add_f32_e32 v30, 1.0, v30
	v_add_f32_e32 v31, 1.0, v31
	v_rcp_f32_e32 v30, v30
	v_rcp_f32_e32 v31, v31
	v_pk_mul_f32 v[16:17], v[28:29], v[16:17]
	v_pk_mul_f32 v[22:23], v[22:23], v[148:149] op_sel_hi:[1,0]
	v_add_u32_e32 v32, 0xa0, v146
	v_pk_mul_f32 v[22:23], v[22:23], v[16:17]
	v_pk_mul_f32 v[16:17], v[26:27], v[30:31]
	v_pk_mul_f32 v[18:19], v[18:19], v[148:149] op_sel_hi:[1,0]
	v_mad_i64_i32 v[32:33], s[26:27], v32, s57, v[150:151]
	v_pk_mul_f32 v[26:27], v[18:19], v[16:17]
	v_lshl_add_u64 v[28:29], v[32:33], 0, v[112:113]
	v_cvt_pk_bf16_f32 v16, v20, v21
	v_cvt_pk_bf16_f32 v17, v22, v23
	v_cvt_pk_bf16_f32 v18, v24, v25
	v_cvt_pk_bf16_f32 v19, v26, v27
	v_pk_mul_f32 v[12:13], v[12:13], v[144:145] op_sel_hi:[1,0]
	global_store_dwordx4 v[28:29], v[16:19], off
	v_pk_mul_f32 v[8:9], v[8:9], v[144:145] op_sel_hi:[1,0]
	v_pk_mul_f32 v[4:5], v[4:5], v[144:145] op_sel_hi:[1,0]
	v_mul_f32_e32 v17, 0xbfb8aa3b, v12
	v_exp_f32_e32 v18, v17
	v_mul_f32_e32 v17, 0xbfb8aa3b, v13
	v_exp_f32_e32 v19, v17
	v_mul_f32_e32 v20, 0xbfb8aa3b, v8
	v_add_f32_e32 v18, 1.0, v18
	v_rcp_f32_e32 v18, v18
	v_add_f32_e32 v19, 1.0, v19
	v_mul_f32_e32 v21, 0xbfb8aa3b, v9
	v_rcp_f32_e32 v19, v19
	v_exp_f32_e32 v20, v20
	v_exp_f32_e32 v21, v21
	v_pk_mul_f32 v[0:1], v[0:1], v[144:145] op_sel_hi:[1,0]
	v_pk_mul_f32 v[12:13], v[12:13], v[18:19]
	v_add_f32_e32 v20, 1.0, v20
	v_add_f32_e32 v21, 1.0, v21
	v_pk_mul_f32 v[4:5], v[4:5], v[12:13]
	v_pk_mul_f32 v[12:13], v[14:15], v[144:145] op_sel_hi:[1,0]
	v_rcp_f32_e32 v20, v20
	v_rcp_f32_e32 v21, v21
	v_mul_f32_e32 v14, 0xbfb8aa3b, v12
	v_mul_f32_e32 v15, 0xbfb8aa3b, v13
	v_exp_f32_e32 v14, v14
	v_exp_f32_e32 v15, v15
	v_pk_mul_f32 v[8:9], v[8:9], v[20:21]
	v_pk_mul_f32 v[10:11], v[10:11], v[144:145] op_sel_hi:[1,0]
	v_pk_mul_f32 v[8:9], v[0:1], v[8:9]
	v_add_f32_e32 v0, 1.0, v14
	v_add_f32_e32 v1, 1.0, v15
	v_mul_f32_e32 v14, 0xbfb8aa3b, v10
	v_mul_f32_e32 v15, 0xbfb8aa3b, v11
	v_exp_f32_e32 v14, v14
	v_exp_f32_e32 v15, v15
	v_rcp_f32_e32 v0, v0
	v_rcp_f32_e32 v1, v1
	v_add_f32_e32 v14, 1.0, v14
	v_add_f32_e32 v15, 1.0, v15
	v_rcp_f32_e32 v14, v14
	v_rcp_f32_e32 v15, v15
	v_pk_mul_f32 v[0:1], v[12:13], v[0:1]
	v_pk_mul_f32 v[6:7], v[6:7], v[144:145] op_sel_hi:[1,0]
	v_add_u32_e32 v16, 0xb0, v146
	v_pk_mul_f32 v[6:7], v[6:7], v[0:1]
	v_pk_mul_f32 v[0:1], v[10:11], v[14:15]
	v_pk_mul_f32 v[2:3], v[2:3], v[144:145] op_sel_hi:[1,0]
	v_mad_i64_i32 v[16:17], s[26:27], v16, s57, v[150:151]
	v_pk_mul_f32 v[10:11], v[2:3], v[0:1]
	v_lshl_add_u64 v[12:13], v[16:17], 0, v[112:113]
	v_cvt_pk_bf16_f32 v0, v4, v5
	v_cvt_pk_bf16_f32 v1, v6, v7
	v_cvt_pk_bf16_f32 v2, v8, v9
	v_cvt_pk_bf16_f32 v3, v10, v11
	s_andn2_b64 vcc, exec, s[0:1]
	s_mov_b64 s[0:1], -1
	global_store_dwordx4 v[12:13], v[0:3], off
	s_cbranch_vccnz .LBB0_1067
	s_andn2_b64 vcc, exec, s[4:5]
	s_cbranch_vccnz .LBB0_1066
	s_barrier
	s_branch .LBB0_1066
